# reverse M/item order in ph_down, ret_kv, dil_attn for cache reuse
# speedup vs baseline: 1.0056x; 1.0056x over previous
; DI void ret_kv_phase(int l, unsigned char* lds_g, LAS unsigned char* lds) {
;     const int tid = opaque_tid(), lane = tid & 63, w = tid >> 6, fr = lane & 15, fq = lane >> 4;
;     const unsigned lbase = (unsigned)(size_t)lds_g;
;     const bf16_t* Z = (const bf16_t*)(arg_ws() + WS_Z); bf16_t* KV = (bf16_t*)(arg_ws() + WS_KV);
;     constexpr int OV = 0, OKF = 128 * RV_PITCH, OKB = OKF + 128 * RK_PITCH;
;     for (int item = opaque_bid(); item < GB * 4 * 32; item += gridDim.x) {
;         const int n = item & 31, h = (item >> 5) & 3, bl = item >> 7;
;         const size_t row0 = (size_t)bl * SEQ + n * 128;
;         const float de_f = arg_in(I_DEC)[(l * 2 + 0) * 4 + h], de_b = arg_in(I_DEC)[(l * 2 + 1) * 4 + h];
;         const float l2f = log1pf(-exp2f(-de_f)) * 1.44269504f, l2b = log1pf(-exp2f(-de_b)) * 1.44269504f;
; #pragma unroll
;         for (int i = 0; i < 8; ++i) { const int id = tid + 512 * i, r = id >> 5, ch = id & 31;
;             const u32x4 v = *(const u32x4*)(Z + (row0 + r) * INW + ZC_RV + h * 256 + ch * 8);
;             *(LAS u32x4*)(lds + OV + r * RV_PITCH + ch * 16) = v; }
; #pragma unroll
;         for (int i = 0; i < 4; ++i) { const int id = tid + 512 * i, r = id >> 4, ch = id & 15;
;             const u32x4 v = *(const u32x4*)(Z + (row0 + r) * INW + ZC_RK + h * 128 + ch * 8);
;             const float sf = fexp2(l2f * (float)(127 - r)), sb = fexp2(l2b * (float)r);
;             u32x4 f, b;
;             f.x = pk2(bflo(v.x) * sf, bfhi(v.x) * sf); f.y = pk2(bflo(v.y) * sf, bfhi(v.y) * sf); f.z = pk2(bflo(v.z) * sf, bfhi(v.z) * sf); f.w = pk2(bflo(v.w) * sf, bfhi(v.w) * sf);
;             b.x = pk2(bflo(v.x) * sb, bfhi(v.x) * sb); b.y = pk2(bflo(v.y) * sb, bfhi(v.y) * sb); b.z = pk2(bflo(v.z) * sb, bfhi(v.z) * sb); b.w = pk2(bflo(v.w) * sb, bfhi(v.w) * sb);
;             *(LAS u32x4*)(lds + OKF + r * RK_PITCH + ch * 16) = f; *(LAS u32x4*)(lds + OKB + r * RK_PITCH + ch * 16) = b; }
;         __syncthreads();
;         f32x4 acc[2][8][2];
; #pragma unroll
;         for (int d = 0; d < 2; ++d)
; #pragma unroll
;             for (int mt = 0; mt < 8; ++mt)
; #pragma unroll
;                 for (int nt = 0; nt < 2; ++nt) acc[d][mt][nt] = (f32x4){0.f, 0.f, 0.f, 0.f};
;         const int q = fr >> 2, p = fr & 3;
; #pragma unroll 1
;         for (int ks = 0; ks < 4; ++ks) {
;             const int tr0 = 32 * ks + 8 * fq + q;
.LBB0_189:
	s_or_b64 exec, exec, s[4:5]
	v_mov_b32_e32 v2, v242
	s_mov_b64 s[8:9], s[0:1]
	s_mov_b64 s[6:7], s[0:1]
	s_sub_i32 s4, 0x1ff, s2
	s_waitcnt lgkmcnt(0)
	s_barrier
	s_cmpk_gt_i32 s4, 0x1ff
	s_cbranch_scc1 .LBB0_194
	v_and_b32_e32 v3, 15, v2
	v_and_b32_e32 v1, 31, v2
	v_lshlrev_b32_e32 v8, 4, v3
	v_readlane_b32 s5, v255, 3
	s_waitcnt vmcnt(8)
	v_lshlrev_b32_e32 v4, 3, v1
	v_lshl_add_u32 v7, v1, 4, 0
	v_add_u32_e32 v1, s5, v8
	v_add_u32_e32 v160, s82, v8
	v_lshlrev_b32_e32 v8, 3, v2
	v_and_b32_e32 v14, 24, v8
	v_ashrrev_i32_e32 v8, 1, v2
	v_and_b32_e32 v8, 0xffffffe0, v8
	s_load_dwordx2 s[8:9], s[8:9], 0xa8
	s_nop 0
	s_load_dwordx2 s[22:23], s[6:7], 0xa8
	v_lshlrev_b32_e32 v6, 3, v3
	v_ashrrev_i32_e32 v9, 31, v8
	v_or_b32_e32 v8, v8, v3
	v_add_u32_e32 v3, 0x200, v2
	v_ashrrev_i32_e32 v146, 4, v2
	v_bfe_u32 v5, v2, 4, 2
	v_bfe_u32 v12, v2, 2, 2
	v_and_b32_e32 v13, 0xffffffc0, v2
	v_ashrrev_i32_e32 v130, 5, v2
	v_add_u32_e32 v17, 0x400, v2
	v_add_u32_e32 v19, 0x600, v2
	v_add_u32_e32 v21, 0x800, v2
	v_add_u32_e32 v22, 0xa00, v2
	v_add_u32_e32 v23, 0xc00, v2
	v_add_u32_e32 v24, 0xe00, v2
	v_sub_u32_e32 v2, 0x7f, v146
	v_ashrrev_i32_e32 v148, 4, v3
	v_cvt_f32_i32_e32 v161, v2
	v_sub_u32_e32 v2, 0x7f, v148
	v_ashrrev_i32_e32 v150, 4, v17
	v_cvt_f32_i32_e32 v164, v2
	v_sub_u32_e32 v2, 0x7f, v150
	v_ashrrev_i32_e32 v152, 4, v19
	v_lshlrev_b32_e32 v10, 3, v5
	v_mov_b32_e32 v11, v0
	v_cvt_f32_i32_e32 v167, v2
	v_sub_u32_e32 v2, 0x7f, v152
	s_waitcnt lgkmcnt(0)
	s_add_u32 s6, s8, 0x16c00000
	v_lshl_add_u64 v[10:11], s[22:23], 0, v[10:11]
	v_ashrrev_i32_e32 v132, 5, v3
	v_cvt_f32_i32_e32 v170, v2
	v_lshlrev_b64 v[2:3], 8, v[8:9]
	s_addc_u32 s7, s9, 0
	v_lshl_add_u64 v[2:3], v[10:11], 0, v[2:3]
	s_mov_b64 s[8:9], 0x29c00000
	v_cvt_f32_i32_e32 v162, v146
	v_cvt_f32_i32_e32 v165, v148
	v_cvt_f32_i32_e32 v168, v150
	v_cvt_f32_i32_e32 v171, v152
	v_lshl_add_u64 v[154:155], v[2:3], 0, s[8:9]
	v_mul_u32_u24_e32 v2, 0x880, v5
	v_mul_u32_u24_e32 v3, 0x110, v12
	v_ashrrev_i32_e32 v134, 5, v17
	v_ashrrev_i32_e32 v136, 5, v19
	v_ashrrev_i32_e32 v138, 5, v21
	v_ashrrev_i32_e32 v140, 5, v22
	v_ashrrev_i32_e32 v142, 5, v23
	v_ashrrev_i32_e32 v144, 5, v24
	v_add3_u32 v173, v2, v3, v14
	v_mul_u32_u24_e32 v2, 0x210, v12
	s_movk_i32 s5, 0x1080
	v_mul_lo_u32 v15, v130, s83
	v_mul_lo_u32 v16, v132, s83
	v_mul_lo_u32 v18, v134, s83
	v_mul_lo_u32 v20, v136, s83
	v_mul_lo_u32 v21, v138, s83
	v_mul_lo_u32 v22, v140, s83
	v_mul_lo_u32 v23, v142, s83
	v_mul_lo_u32 v24, v144, s83
	v_mad_u32_u24 v2, v5, s5, v2
	v_ashrrev_i32_e32 v131, 31, v130
	v_ashrrev_i32_e32 v133, 31, v132
	v_ashrrev_i32_e32 v135, 31, v134
	v_ashrrev_i32_e32 v137, 31, v136
	v_ashrrev_i32_e32 v139, 31, v138
	v_ashrrev_i32_e32 v141, 31, v140
	v_ashrrev_i32_e32 v143, 31, v142
	v_ashrrev_i32_e32 v145, 31, v144
	v_ashrrev_i32_e32 v147, 31, v146
	v_mul_lo_u32 v163, v146, s84
	v_ashrrev_i32_e32 v149, 31, v148
	v_mul_lo_u32 v166, v148, s84
	v_ashrrev_i32_e32 v151, 31, v150
	v_mul_lo_u32 v169, v150, s84
	v_ashrrev_i32_e32 v153, 31, v152
	v_mul_lo_u32 v172, v152, s84
	v_add3_u32 v174, v2, v13, v14
	v_lshlrev_b32_e32 v156, 1, v4
	v_add_u32_e32 v175, v7, v15
	v_add_u32_e32 v176, v7, v16
	v_add_u32_e32 v177, v7, v18
	v_add_u32_e32 v178, v7, v20
	v_add_u32_e32 v179, v7, v21
	v_add_u32_e32 v180, v7, v22
	v_add_u32_e32 v181, v7, v23
	v_add_u32_e32 v182, v7, v24
	v_lshlrev_b32_e32 v158, 1, v6

; DI f32x4 mfma16(bf16x8 a, bf16x8 b, f32x4 c) { return __builtin_amdgcn_mfma_f32_16x16x32_bf16(a, b, c, 0, 0, 0); }
; DI void ret_kv_phase(int l, unsigned char* lds_g, LAS unsigned char* lds) {
;     ...
;         const int q = fr >> 2, p = fr & 3;
; #pragma unroll 1
;         for (int ks = 0; ks < 4; ++ks) {
;             const int tr0 = 32 * ks + 8 * fq + q;
;             bf16x8 Bv[2];
; #pragma unroll
;             for (int nt = 0; nt < 2; ++nt) { const unsigned ad = lbase + OV + tr0 * RV_PITCH + (32 * w + 16 * nt + 4 * p) * 2; Bv[nt] = tr_frag(ad, ad + 4 * RV_PITCH); }
; #pragma unroll
;             for (int d = 0; d < 2; ++d) { const unsigned ad = lbase + (d ? OKB : OKF) + tr0 * RK_PITCH + (4 * p) * 2; bf16x8 Ak[8]; tr8(ad, ad + 4 * RK_PITCH, Ak);
; #pragma unroll
;                 for (int mt = 0; mt < 8; ++mt)
; #pragma unroll
;                     for (int nt = 0; nt < 2; ++nt) acc[d][mt][nt] = mfma16(Ak[mt], Bv[nt], acc[d][mt][nt]); }
;         }
.LBB0_192:
	s_cmp_lg_u32 0, -1
	s_cselect_b32 s8, 0, 0
	v_add_u32_e32 v183, s8, v157
	v_add_u32_e32 v188, 0x840, v183
	ds_read_b64_tr_b16 v[184:185], v183
	ds_read_b64_tr_b16 v[186:187], v188
	s_waitcnt lgkmcnt(0)
	v_add_u32_e32 v192, s8, v159
	v_add_u32_e32 v193, 32, v183
	v_add_u32_e32 v195, 0x860, v183
	ds_read_b64_tr_b16 v[188:189], v193
	ds_read_b64_tr_b16 v[190:191], v195
	s_waitcnt lgkmcnt(0)
	v_add_u32_e32 v204, 0x10800, v192
	v_add_u32_e32 v205, 0x10c40, v192
	ds_read_b64_tr_b16 v[214:215], v204
	ds_read_b64_tr_b16 v[216:217], v205
	ds_read_b64_tr_b16 v[210:211], v204 offset:32
	ds_read_b64_tr_b16 v[212:213], v205 offset:32
	ds_read_b64_tr_b16 v[206:207], v204 offset:64
	ds_read_b64_tr_b16 v[208:209], v205 offset:64
	ds_read_b64_tr_b16 v[200:201], v204 offset:96
	ds_read_b64_tr_b16 v[202:203], v205 offset:96
	s_waitcnt lgkmcnt(0)
	v_add_u32_e32 v183, 0x10880, v192
	v_mfma_f32_16x16x32_bf16 v[126:129], v[214:217], v[184:187], v[126:129]
	v_add_u32_e32 v193, 0x10cc0, v192
	s_add_i32 s5, s5, -1
	v_add_u32_e32 v159, 0x2200, v159
	v_mfma_f32_16x16x32_bf16 v[106:109], v[214:217], v[188:191], v[106:109]
	s_cmp_eq_u32 s5, 0
	v_add_u32_e32 v157, 0x4200, v157
	v_mfma_f32_16x16x32_bf16 v[122:125], v[210:213], v[184:187], v[122:125]
	v_mfma_f32_16x16x32_bf16 v[98:101], v[210:213], v[188:191], v[98:101]
	v_mfma_f32_16x16x32_bf16 v[118:121], v[206:209], v[184:187], v[118:121]
	v_mfma_f32_16x16x32_bf16 v[90:93], v[206:209], v[188:191], v[90:93]
	v_mfma_f32_16x16x32_bf16 v[114:117], v[200:203], v[184:187], v[114:117]
	v_mfma_f32_16x16x32_bf16 v[82:85], v[200:203], v[188:191], v[82:85]
	ds_read_b64_tr_b16 v[214:215], v183
	ds_read_b64_tr_b16 v[216:217], v193
	ds_read_b64_tr_b16 v[210:211], v183 offset:32
	ds_read_b64_tr_b16 v[212:213], v193 offset:32
	ds_read_b64_tr_b16 v[206:207], v183 offset:64
	ds_read_b64_tr_b16 v[208:209], v193 offset:64
	ds_read_b64_tr_b16 v[200:201], v183 offset:96
	ds_read_b64_tr_b16 v[202:203], v193 offset:96
	s_waitcnt lgkmcnt(0)
	v_add_u32_e32 v183, 0x19000, v192
	v_add_u32_e32 v193, 0x19440, v192
	v_mfma_f32_16x16x32_bf16 v[110:113], v[214:217], v[184:187], v[110:113]
	v_mfma_f32_16x16x32_bf16 v[78:81], v[214:217], v[188:191], v[78:81]
	v_mfma_f32_16x16x32_bf16 v[102:105], v[210:213], v[184:187], v[102:105]
	v_mfma_f32_16x16x32_bf16 v[74:77], v[210:213], v[188:191], v[74:77]
	v_mfma_f32_16x16x32_bf16 v[94:97], v[206:209], v[184:187], v[94:97]
	v_mfma_f32_16x16x32_bf16 v[70:73], v[206:209], v[188:191], v[70:73]
	v_mfma_f32_16x16x32_bf16 v[86:89], v[200:203], v[184:187], v[86:89]
	v_mfma_f32_16x16x32_bf16 v[66:69], v[200:203], v[188:191], v[66:69]
	ds_read_b64_tr_b16 v[214:215], v183
	ds_read_b64_tr_b16 v[216:217], v193
	ds_read_b64_tr_b16 v[210:211], v183 offset:32
	ds_read_b64_tr_b16 v[212:213], v193 offset:32
	ds_read_b64_tr_b16 v[206:207], v183 offset:64
	ds_read_b64_tr_b16 v[208:209], v193 offset:64
	ds_read_b64_tr_b16 v[200:201], v183 offset:96
	ds_read_b64_tr_b16 v[202:203], v193 offset:96
	s_waitcnt lgkmcnt(0)
	v_add_u32_e32 v183, 0x19080, v192
	v_add_u32_e32 v192, 0x194c0, v192
	v_mfma_f32_16x16x32_bf16 v[62:65], v[214:217], v[184:187], v[62:65]
	v_mfma_f32_16x16x32_bf16 v[34:37], v[214:217], v[188:191], v[34:37]
	v_mfma_f32_16x16x32_bf16 v[54:57], v[210:213], v[184:187], v[54:57]
	v_mfma_f32_16x16x32_bf16 v[26:29], v[210:213], v[188:191], v[26:29]
	v_mfma_f32_16x16x32_bf16 v[50:53], v[206:209], v[184:187], v[50:53]
	v_mfma_f32_16x16x32_bf16 v[18:21], v[206:209], v[188:191], v[18:21]
	v_mfma_f32_16x16x32_bf16 v[46:49], v[200:203], v[184:187], v[46:49]
	v_mfma_f32_16x16x32_bf16 v[14:17], v[200:203], v[188:191], v[14:17]
	ds_read_b64_tr_b16 v[214:215], v183
	ds_read_b64_tr_b16 v[216:217], v192
	ds_read_b64_tr_b16 v[210:211], v183 offset:32
	ds_read_b64_tr_b16 v[212:213], v192 offset:32
	ds_read_b64_tr_b16 v[206:207], v183 offset:64
	ds_read_b64_tr_b16 v[208:209], v192 offset:64
	ds_read_b64_tr_b16 v[200:201], v183 offset:96
	ds_read_b64_tr_b16 v[202:203], v192 offset:96
	s_waitcnt lgkmcnt(0)
	s_nop 0
	v_mfma_f32_16x16x32_bf16 v[38:41], v[214:217], v[184:187], v[38:41]
	v_mfma_f32_16x16x32_bf16 v[10:13], v[214:217], v[188:191], v[10:13]
	v_mfma_f32_16x16x32_bf16 v[30:33], v[210:213], v[184:187], v[30:33]
	v_mfma_f32_16x16x32_bf16 v[6:9], v[210:213], v[188:191], v[6:9]
	v_mfma_f32_16x16x32_bf16 v[22:25], v[206:209], v[184:187], v[22:25]
	v_mfma_f32_16x16x32_bf16 v[2:5], v[206:209], v[188:191], v[2:5]
	v_mfma_f32_16x16x32_bf16 v[58:61], v[200:203], v[184:187], v[58:61]
	v_mfma_f32_16x16x32_bf16 v[42:45], v[200:203], v[188:191], v[42:45]
	s_cbranch_scc0 .LBB0_192
; DI int opaque_bid() { int t = blockIdx.x; asm volatile("" : "+s"(t)); return t; }
; DI unsigned pk2(float lo, float hi) { unsigned r; asm("v_cvt_pk_bf16_f32 %0, %1, %2" : "=v"(r) : "v"(lo), "v"(hi)); return r; }
; DI void ret_kv_phase(int l, unsigned char* lds_g, LAS unsigned char* lds) {
;     ...
;     for (int item = opaque_bid(); item < GB * 4 * 32; item += gridDim.x) {
;     ...
; #pragma unroll
;         for (int d = 0; d < 2; ++d)
; #pragma unroll
;             for (int nt = 0; nt < 2; ++nt)
; #pragma unroll
;                 for (int mt = 0; mt < 8; ++mt)
;                     { u32x2 o; o.x = pk2(acc[d][mt][nt][0], acc[d][mt][nt][1]); o.y = pk2(acc[d][mt][nt][2], acc[d][mt][nt][3]);
;                       *(u32x2*)(KV + (((size_t)item * 2 + d) * 256 + 32 * w + 16 * nt + fr) * 128 + 16 * mt + 4 * fq) = o; }
;         __syncthreads();
	s_ashr_i32 s5, s4, 31
	s_lshl_b64 s[8:9], s[4:5], 17
	v_lshl_add_u64 v[184:185], v[154:155], 0, s[8:9]
	v_cvt_pk_bf16_f32 v86, v86, v87
	v_cvt_pk_bf16_f32 v87, v88, v89
	v_add_co_u32_e32 v88, vcc, s77, v184
	s_mov_b32 s5, 0x10000
	s_nop 0
	v_addc_co_u32_e32 v89, vcc, 0, v185, vcc
	v_cvt_pk_bf16_f32 v62, v62, v63
	v_cvt_pk_bf16_f32 v63, v64, v65
	v_add_co_u32_e32 v64, vcc, s5, v184
	v_cvt_pk_bf16_f32 v66, v66, v67
	s_mov_b32 s5, 0x11000
	s_nop 0
	v_addc_co_u32_e32 v65, vcc, 0, v185, vcc
	v_cvt_pk_bf16_f32 v22, v22, v23
	v_cvt_pk_bf16_f32 v23, v24, v25
	global_store_dwordx2 v[184:185], v[86:87], off offset:224
	v_cvt_pk_bf16_f32 v86, v106, v107
	v_cvt_pk_bf16_f32 v87, v108, v109
	v_cvt_pk_bf16_f32 v67, v68, v69
	global_store_dwordx2 v[88:89], v[66:67], off offset:224
	v_add_co_u32_e32 v66, vcc, s5, v184
	global_store_dwordx2 v[64:65], v[22:23], off offset:192
	v_cvt_pk_bf16_f32 v22, v58, v59
	v_cvt_pk_bf16_f32 v23, v60, v61
	s_sub_i32 s4, s4, s14
	global_store_dwordx2 v[88:89], v[86:87], off
	v_cvt_pk_bf16_f32 v86, v98, v99
	v_cvt_pk_bf16_f32 v87, v100, v101
	v_addc_co_u32_e32 v67, vcc, 0, v185, vcc
	global_store_dwordx2 v[64:65], v[22:23], off offset:224
	v_cvt_pk_bf16_f32 v22, v34, v35
	v_cvt_pk_bf16_f32 v23, v36, v37
	v_cvt_pk_bf16_f32 v2, v2, v3
	v_cvt_pk_bf16_f32 v3, v4, v5
	s_cmp_lt_i32 s4, 0
	v_cvt_pk_bf16_f32 v126, v126, v127
	v_cvt_pk_bf16_f32 v127, v128, v129
	global_store_dwordx2 v[184:185], v[126:127], off
	v_cvt_pk_bf16_f32 v122, v122, v123
	v_cvt_pk_bf16_f32 v123, v124, v125
	global_store_dwordx2 v[184:185], v[122:123], off offset:32
	v_cvt_pk_bf16_f32 v118, v118, v119
	v_cvt_pk_bf16_f32 v119, v120, v121
	global_store_dwordx2 v[184:185], v[118:119], off offset:64
	v_cvt_pk_bf16_f32 v114, v114, v115
	v_cvt_pk_bf16_f32 v115, v116, v117
	global_store_dwordx2 v[184:185], v[114:115], off offset:96
	v_cvt_pk_bf16_f32 v110, v110, v111
	v_cvt_pk_bf16_f32 v111, v112, v113
	global_store_dwordx2 v[184:185], v[110:111], off offset:128
	v_cvt_pk_bf16_f32 v102, v102, v103
	v_cvt_pk_bf16_f32 v103, v104, v105
	global_store_dwordx2 v[184:185], v[102:103], off offset:160
	v_cvt_pk_bf16_f32 v94, v94, v95
	v_cvt_pk_bf16_f32 v95, v96, v97
	global_store_dwordx2 v[184:185], v[94:95], off offset:192
	global_store_dwordx2 v[88:89], v[86:87], off offset:32
	v_cvt_pk_bf16_f32 v86, v90, v91
	v_cvt_pk_bf16_f32 v87, v92, v93
	global_store_dwordx2 v[88:89], v[86:87], off offset:64
	v_cvt_pk_bf16_f32 v82, v82, v83
	v_cvt_pk_bf16_f32 v83, v84, v85
	global_store_dwordx2 v[88:89], v[82:83], off offset:96
	v_cvt_pk_bf16_f32 v78, v78, v79
	v_cvt_pk_bf16_f32 v79, v80, v81
	global_store_dwordx2 v[88:89], v[78:79], off offset:128
	v_cvt_pk_bf16_f32 v74, v74, v75
	v_cvt_pk_bf16_f32 v75, v76, v77
	global_store_dwordx2 v[88:89], v[74:75], off offset:160
	v_cvt_pk_bf16_f32 v70, v70, v71
	v_cvt_pk_bf16_f32 v71, v72, v73
	global_store_dwordx2 v[88:89], v[70:71], off offset:192
	global_store_dwordx2 v[66:67], v[62:63], off offset:-4096
	v_cvt_pk_bf16_f32 v54, v54, v55
	v_cvt_pk_bf16_f32 v55, v56, v57
	global_store_dwordx2 v[64:65], v[54:55], off offset:32
	v_cvt_pk_bf16_f32 v50, v50, v51
	v_cvt_pk_bf16_f32 v51, v52, v53
	global_store_dwordx2 v[64:65], v[50:51], off offset:64
	v_cvt_pk_bf16_f32 v46, v46, v47
	v_cvt_pk_bf16_f32 v47, v48, v49
	global_store_dwordx2 v[64:65], v[46:47], off offset:96
	v_cvt_pk_bf16_f32 v38, v38, v39
	v_cvt_pk_bf16_f32 v39, v40, v41
	global_store_dwordx2 v[64:65], v[38:39], off offset:128
	v_cvt_pk_bf16_f32 v30, v30, v31
	v_cvt_pk_bf16_f32 v31, v32, v33
	global_store_dwordx2 v[64:65], v[30:31], off offset:160
	global_store_dwordx2 v[66:67], v[22:23], off
	v_cvt_pk_bf16_f32 v22, v26, v27
	v_cvt_pk_bf16_f32 v23, v28, v29
	global_store_dwordx2 v[66:67], v[22:23], off offset:32
	v_cvt_pk_bf16_f32 v18, v18, v19
	v_cvt_pk_bf16_f32 v19, v20, v21
	global_store_dwordx2 v[66:67], v[18:19], off offset:64
	v_cvt_pk_bf16_f32 v14, v14, v15
	v_cvt_pk_bf16_f32 v15, v16, v17
	global_store_dwordx2 v[66:67], v[14:15], off offset:96
	v_cvt_pk_bf16_f32 v10, v10, v11
	v_cvt_pk_bf16_f32 v11, v12, v13
	global_store_dwordx2 v[66:67], v[10:11], off offset:128
	v_cvt_pk_bf16_f32 v6, v6, v7
	v_cvt_pk_bf16_f32 v7, v8, v9
	global_store_dwordx2 v[66:67], v[6:7], off offset:160
	global_store_dwordx2 v[66:67], v[2:3], off offset:192
	v_cvt_pk_bf16_f32 v2, v42, v43
	v_cvt_pk_bf16_f32 v3, v44, v45
	global_store_dwordx2 v[66:67], v[2:3], off offset:224
	s_barrier
	s_cbranch_scc0 .LBB0_191

; DI int opaque_bid() { int t = blockIdx.x; asm volatile("" : "+s"(t)); return t; }
; template <bool STORE = true> DI void dil_attn_phase(int l, unsigned char* lds_g, LAS unsigned char* lds) {
;     ...
;     int item; { const int bx = opaque_bid(), G = (int)gridDim.x; item = (G % 8 == 0) ? (bx % 8) * (G / 8) + bx / 8 : bx; }
;     if (item >= NITEM) return;
.LBB0_196:
	s_ashr_i32 s12, s17, 31
	s_lshr_b32 s12, s12, 29
	s_add_i32 s12, s17, s12
	s_ashr_i32 s18, s12, 3
	s_and_b32 s12, s12, -8
	s_sub_i32 s12, s17, s12
	v_readlane_b32 s17, v255, 2
	s_mul_i32 s12, s12, s17
	s_add_i32 s17, s12, s18
	s_sub_i32 s17, 0x5ff, s17
	s_cmpk_gt_i32 s17, 0x5ff
	s_cbranch_scc1 .LBB0_313

; #define LAS __attribute__((address_space(3)))
; template <bool STORE = true> DI void dil_attn_phase(int l, unsigned char* lds_g, LAS unsigned char* lds) {
;     const int tid = opaque_tid(), lane = tid & 63, w = tid >> 6, fr = lane & 15, fq = lane >> 4;
;     const unsigned lbase = (unsigned)(size_t)lds_g;
;     bf16_t* Z = (bf16_t*)(arg_ws() + WS_Z); float* LSE = (float*)(arg_ws() + WS_LSE);
;     const float* bt = (const float*)(arg_ws() + WS_BIAS);
;     const float* qn = arg_in(I_QN) + l * 128; const float* kn = arg_in(I_KN) + l * 128;
;     constexpr int KP = 272, OK = 0, OV = 256 * KP, OB = 2 * 256 * KP, NITEM = GB * 12 * 32;
;     int item; { const int bx = opaque_bid(), G = (int)gridDim.x; item = (G % 8 == 0) ? (bx % 8) * (G / 8) + bx / 8 : bx; }
;     if (item >= NITEM) return;
;     u32x4 kraw[8], vraw[8];
;     DilIt it = dil_decode(item);
;     dil_issue(Z, it, tid, kraw, vraw);
;     for (;;) {
;     ...
;         u32x4 qraw[4]; dil_issue_q(Z, it, w, fr, fq, qraw);
; #pragma unroll
;         for (int i = 0; i < 8; ++i) { const int id = tid + 512 * i, kk = id >> 4, ch = id & 15;
;             const u32x4 kv = kraw[i];
;             float f[8] = {bflo(kv.x), bfhi(kv.x), bflo(kv.y), bfhi(kv.y), bflo(kv.z), bfhi(kv.z), bflo(kv.w), bfhi(kv.w)};
;             float ss = 0.f;
; #pragma unroll
;             for (int e = 0; e < 8; ++e) ss += f[e] * f[e];
;             ss += __shfl_xor(ss, 1); ss += __shfl_xor(ss, 2); ss += __shfl_xor(ss, 4); ss += __shfl_xor(ss, 8);
;             const float rs = __builtin_amdgcn_rsqf(ss * (1.0f / 128.0f) + EPS);
;             const f32x4 g0 = *(const f32x4*)(kn + ch * 8), g1 = *(const f32x4*)(kn + ch * 8 + 4);
;             u32x4 ko; ko.x = pk2(f[0] * rs * g0[0], f[1] * rs * g0[1]); ko.y = pk2(f[2] * rs * g0[2], f[3] * rs * g0[3]); ko.z = pk2(f[4] * rs * g1[0], f[5] * rs * g1[1]); ko.w = pk2(f[6] * rs * g1[2], f[7] * rs * g1[3]);
;             *(LAS u32x4*)(lds + OK + kk * KP + ch * 16) = ko; *(LAS u32x4*)(lds + OV + kk * KP + ch * 16) = vraw[i];
;             asm volatile("" ::: "memory"); }
;         if (tid < 129) *(LAS float*)(lds + OB + tid * 4) = bt[hh * 129 + tid];
;         const size_t qrow = rowb + (size_t)(i0 + 16 * w + fr) * d;
;         bf16x8 Qf[4];
;         {
;             float ss = 0.f;
; #pragma unroll
;             for (int ks = 0; ks < 4; ++ks) { const u32x4 v = qraw[ks];
.LBB0_213:
	s_or_b64 exec, exec, s[4:5]
	v_and_b32_e32 v77, 64, v249
	v_xor_b32_e32 v76, 1, v249
	v_add_u32_e32 v80, 64, v77
	v_cmp_lt_i32_e32 vcc, v76, v80
	s_and_b64 s[4:5], s[58:59], exec
	s_cselect_b32 s18, 4, 16
	v_cndmask_b32_e32 v76, v249, v76, vcc
	v_lshlrev_b32_e32 v148, 2, v76
	v_xor_b32_e32 v76, 2, v249
	s_and_b64 s[4:5], s[60:61], exec
	v_cmp_lt_i32_e32 vcc, v76, v80
	s_cselect_b32 s65, 1, s18
	s_add_u32 s54, s54, 0x38c00000
	v_cndmask_b32_e32 v76, v249, v76, vcc
	s_addc_u32 s55, s55, 0
	v_lshlrev_b32_e32 v149, 2, v76
	v_xor_b32_e32 v76, 4, v249
	s_add_u32 s56, s56, 0x300000
	v_cmp_lt_i32_e32 vcc, v76, v80
	s_addc_u32 s57, s57, 0
	s_add_u32 s8, s8, s38
	v_cndmask_b32_e32 v76, v249, v76, vcc
	v_lshlrev_b32_e32 v150, 2, v76
	v_xor_b32_e32 v76, 8, v249
	s_addc_u32 s9, s9, s39
	v_cmp_lt_i32_e32 vcc, v76, v80
	v_and_b32_e32 v3, 15, v138
	s_add_u32 s4, s6, s38
	v_cndmask_b32_e32 v76, v249, v76, vcc
	s_addc_u32 s5, s7, s39
	v_lshlrev_b32_e32 v151, 2, v76
	v_lshlrev_b32_e32 v76, 5, v3
	v_mov_b32_e32 v77, v0
	v_bfe_u32 v78, v138, 4, 2
	v_lshl_add_u64 v[118:119], s[4:5], 0, v[76:77]
	v_lshlrev_b32_e32 v76, 4, v3
	s_add_i32 s4, 0, 0x11000
	v_add_u32_e32 v152, 0, v76
	v_add_u32_e32 v153, s4, v76
	v_lshlrev_b32_e32 v76, 5, v78
	v_mul_lo_u32 v163, v1, s84
	v_xor_b32_e32 v1, 16, v249
	v_lshl_add_u64 v[120:121], s[8:9], 0, v[76:77]
	v_lshlrev_b32_e32 v76, 2, v78
	v_cmp_lt_i32_e32 vcc, v1, v80
	v_ashrrev_i32_e32 v2, 2, v138
	v_sub_u32_e32 v3, v76, v3
	v_cndmask_b32_e32 v1, v249, v1, vcc
	v_and_b32_e32 v79, -16, v2
	v_subrev_u32_e32 v155, 64, v3
	v_bfe_u32 v3, v138, 2, 2
	s_cmp_lg_u32 0, -1
	v_lshlrev_b32_e32 v164, 2, v1
	v_xor_b32_e32 v1, 32, v249
	v_bfi_b32 v147, -16, v2, v138
	v_or3_b32 v3, v79, v3, v76
	s_cselect_b32 s6, 0, 0
	v_cmp_lt_i32_e32 vcc, v1, v80
	v_lshlrev_b32_e32 v2, 3, v78
	v_lshlrev_b32_e32 v81, 2, v138
	v_and_b32_e32 v69, 24, v69
	s_add_i32 s8, s6, 0x11000
	v_cndmask_b32_e32 v1, v249, v1, vcc
	v_mul_lo_u32 v166, v147, s84
	v_mul_lo_u32 v3, v3, s84
	v_lshl_add_u32 v154, v78, 4, 0
	v_mul_lo_u32 v156, v68, s84
	v_mul_lo_u32 v157, v70, s84
	v_mul_lo_u32 v158, v71, s84
	v_mul_lo_u32 v159, v72, s84
	v_mul_lo_u32 v160, v73, s84
	v_mul_lo_u32 v161, v74, s84
	v_mul_lo_u32 v162, v75, s84
	v_lshlrev_b32_e32 v165, 2, v1
	v_add_u32_e32 v1, 0x1100, v166
	v_add_u32_e32 v68, 0x2200, v166
	v_add_u32_e32 v70, 0x3300, v166
	v_add_u32_e32 v71, 0x4400, v166
	v_add_u32_e32 v72, 0x5500, v166
	v_add_u32_e32 v73, 0x6600, v166
	v_add_u32_e32 v74, 0x7700, v166
	v_add_u32_e32 v75, 0x8800, v166
	v_add3_u32 v167, v69, s8, v3
	v_lshlrev_b32_e32 v122, 1, v2
	v_add_u32_e32 v2, 0, v81
	v_cmp_gt_i32_e64 s[4:5], s89, v138
	v_cmp_eq_u32_e64 s[6:7], 0, v78
	v_add_u32_e32 v168, 0x1100, v167
	v_add_u32_e32 v169, 0x80, v167
	v_add_u32_e32 v170, 0x1180, v167
	v_add_u32_e32 v171, 0x2200, v167
	v_add_u32_e32 v172, 0x3300, v167
	v_add_u32_e32 v173, 0x2280, v167
	v_add_u32_e32 v174, 0x3380, v167
	v_add_u32_e32 v175, 0x4400, v167
	v_add_u32_e32 v176, 0x5500, v167
	v_add_u32_e32 v177, 0x4480, v167
	v_add_u32_e32 v178, 0x5580, v167
	v_add_u32_e32 v179, 0x6600, v167
	v_add_u32_e32 v180, 0x7700, v167
	v_add_u32_e32 v181, 0x6680, v167
	v_add_u32_e32 v182, 0x7780, v167
	v_add_u32_e32 v183, 0x8800, v167
	v_add_u32_e32 v184, 0x8880, v167
	s_sub_i32 s64, s17, s14
	v_add_u32_e32 v185, 0x22000, v2
	v_add_u32_e32 v186, v154, v1
	v_add_u32_e32 v187, v154, v68
	v_add_u32_e32 v188, v154, v70
	v_add_u32_e32 v189, v154, v71
	v_add_u32_e32 v190, v154, v72
	v_add_u32_e32 v191, v154, v73
	v_add_u32_e32 v192, v154, v74
	v_add_u32_e32 v193, v154, v75
	v_lshlrev_b32_e32 v124, 1, v76
	s_branch .LBB0_215

; DI unsigned pk2(float lo, float hi) { unsigned r; asm("v_cvt_pk_bf16_f32 %0, %1, %2" : "=v"(r) : "v"(lo), "v"(hi)); return r; }
; DI float bflo(unsigned u) { return __uint_as_float(u << 16); }
; DI float bfhi(unsigned u) { return __uint_as_float(u & 0xffff0000u); }
; template <bool STORE = true> DI void dil_attn_phase(int l, unsigned char* lds_g, LAS unsigned char* lds) {
;     ...
;         {
;             float ss = 0.f;
; #pragma unroll
;             for (int ks = 0; ks < 4; ++ks) { const u32x4 v = qraw[ks];
;                 ss += bflo(v.x) * bflo(v.x) + bfhi(v.x) * bfhi(v.x) + bflo(v.y) * bflo(v.y) + bfhi(v.y) * bfhi(v.y) + bflo(v.z) * bflo(v.z) + bfhi(v.z) * bfhi(v.z) + bflo(v.w) * bflo(v.w) + bfhi(v.w) * bfhi(v.w); }
;             ss += __shfl_xor(ss, 16); ss += __shfl_xor(ss, 32);
;             const float rs = __builtin_amdgcn_rsqf(ss * (1.0f / 128.0f) + EPS) * 0.08838834764831845f;
; #pragma unroll
;             for (int ks = 0; ks < 4; ++ks) { const u32x4 v = qraw[ks]; const f32x4 g0 = *(const f32x4*)(qn + 32 * ks + 8 * fq), g1 = *(const f32x4*)(qn + 32 * ks + 8 * fq + 4);
;                 u32x4 o; o.x = pk2(bflo(v.x) * rs * g0[0], bfhi(v.x) * rs * g0[1]); o.y = pk2(bflo(v.y) * rs * g0[2], bfhi(v.y) * rs * g0[3]);
;                 o.z = pk2(bflo(v.z) * rs * g1[0], bfhi(v.z) * rs * g1[1]); o.w = pk2(bflo(v.w) * rs * g1[2], bfhi(v.w) * rs * g1[3]); Qf[ks] = as_frag(o); }
;         }
;         __syncthreads();
;         const int nitem = item + (int)gridDim.x; const bool has_next = nitem < NITEM;
.LBB0_217:
	s_or_b64 exec, exec, s[8:9]
	global_load_dwordx4 v[84:87], v[120:121], off offset:16
	global_load_dwordx4 v[88:91], v[120:121], off
	v_and_b32_e32 v117, 0xffff0000, v80
	v_and_b32_e32 v203, 0xffff0000, v76
	v_lshlrev_b32_e32 v1, 16, v80
	v_mul_f32_e32 v2, v117, v117
	v_lshlrev_b32_e32 v202, 16, v76
	v_mul_f32_e32 v3, v203, v203
	v_fmac_f32_e32 v2, v1, v1
	v_lshlrev_b32_e32 v123, 16, v81
	v_fmac_f32_e32 v3, v202, v202
	v_lshlrev_b32_e32 v204, 16, v77
	v_fmac_f32_e32 v2, v123, v123
	v_and_b32_e32 v127, 0xffff0000, v81
	v_lshlrev_b32_e32 v129, 16, v82
	v_and_b32_e32 v195, 0xffff0000, v82
	v_lshlrev_b32_e32 v200, 16, v83
	v_and_b32_e32 v201, 0xffff0000, v83
	v_fmac_f32_e32 v3, v204, v204
	global_load_dwordx4 v[80:83], v[120:121], off offset:144
	global_load_dwordx4 v[92:95], v[120:121], off offset:128
	v_and_b32_e32 v205, 0xffff0000, v77
	v_fmac_f32_e32 v2, v127, v127
	v_fmac_f32_e32 v3, v205, v205
	v_lshlrev_b32_e32 v206, 16, v78
	v_fmac_f32_e32 v2, v129, v129
	v_fmac_f32_e32 v3, v206, v206
	v_and_b32_e32 v207, 0xffff0000, v78
	v_fmac_f32_e32 v2, v195, v195
	v_fmac_f32_e32 v3, v207, v207
	v_lshlrev_b32_e32 v208, 16, v79
	v_fmac_f32_e32 v2, v200, v200
	v_fmac_f32_e32 v3, v208, v208
	v_and_b32_e32 v209, 0xffff0000, v79
	v_fmac_f32_e32 v2, v201, v201
	v_fmac_f32_e32 v3, v209, v209
	v_add_f32_e32 v102, v2, v3
	v_and_b32_e32 v3, 0xffff0000, v72
	v_and_b32_e32 v2, 0xffff0000, v68
	v_lshlrev_b32_e32 v109, 16, v72
	v_lshlrev_b32_e32 v108, 16, v68
	v_pk_mul_f32 v[76:77], v[2:3], v[2:3]
	v_lshlrev_b32_e32 v111, 16, v73
	v_pk_fma_f32 v[100:101], v[108:109], v[108:109], v[76:77]
	global_load_dwordx4 v[96:99], v[120:121], off offset:272
	global_load_dwordx4 v[76:79], v[120:121], off offset:256
	v_lshlrev_b32_e32 v110, 16, v69
	v_pk_fma_f32 v[100:101], v[110:111], v[110:111], v[100:101]
	v_and_b32_e32 v113, 0xffff0000, v73
	v_and_b32_e32 v112, 0xffff0000, v69
	v_pk_fma_f32 v[68:69], v[112:113], v[112:113], v[100:101]
	v_lshlrev_b32_e32 v115, 16, v74
	v_lshlrev_b32_e32 v114, 16, v70
	v_pk_fma_f32 v[68:69], v[114:115], v[114:115], v[68:69]
	v_and_b32_e32 v133, 0xffff0000, v74
	v_and_b32_e32 v132, 0xffff0000, v70
	global_load_dwordx4 v[104:107], v[120:121], off offset:384
	v_pk_fma_f32 v[68:69], v[132:133], v[132:133], v[68:69]
	v_lshlrev_b32_e32 v135, 16, v75
	v_lshlrev_b32_e32 v134, 16, v71
	v_pk_fma_f32 v[68:69], v[134:135], v[134:135], v[68:69]
	v_and_b32_e32 v137, 0xffff0000, v75
	v_and_b32_e32 v136, 0xffff0000, v71
	v_pk_fma_f32 v[68:69], v[136:137], v[136:137], v[68:69]
	s_cmp_gt_i32 s64, -1
	v_add_f32_e32 v68, v102, v68
	global_load_dwordx4 v[100:103], v[120:121], off offset:400
	v_add_f32_e32 v68, v68, v69
	ds_bpermute_b32 v69, v164, v68
	s_cselect_b64 s[58:59], -1, 0
	s_cmp_lt_i32 s64, 0
	s_waitcnt lgkmcnt(0)
	s_barrier
; DI unsigned pk2(float lo, float hi) { unsigned r; asm("v_cvt_pk_bf16_f32 %0, %1, %2" : "=v"(r) : "v"(lo), "v"(hi)); return r; }
; DI float bflo(unsigned u) { return __uint_as_float(u << 16); }
; DI float bfhi(unsigned u) { return __uint_as_float(u & 0xffff0000u); }
; DI void dil_issue(const bf16_t* Z, const DilIt& it, int tid, u32x4 (&kraw)[8], u32x4 (&vraw)[8]) {
; #pragma unroll
;     for (int i = 0; i < 8; ++i) { const int id = tid + 512 * i, kk = id >> 4, ch = id & 15; const int j = it.i0 - 64 + kk; const bool ok = (j >= 0) && (j < it.L);
;         kraw[i] = (u32x4){0u, 0u, 0u, 0u}; vraw[i] = (u32x4){0u, 0u, 0u, 0u};
; template <bool STORE = true> DI void dil_attn_phase(int l, unsigned char* lds_g, LAS unsigned char* lds) {
;     ...
;             ss += __shfl_xor(ss, 16); ss += __shfl_xor(ss, 32);
;             const float rs = __builtin_amdgcn_rsqf(ss * (1.0f / 128.0f) + EPS) * 0.08838834764831845f;
; #pragma unroll
;             for (int ks = 0; ks < 4; ++ks) { const u32x4 v = qraw[ks]; const f32x4 g0 = *(const f32x4*)(qn + 32 * ks + 8 * fq), g1 = *(const f32x4*)(qn + 32 * ks + 8 * fq + 4);
;                 u32x4 o; o.x = pk2(bflo(v.x) * rs * g0[0], bfhi(v.x) * rs * g0[1]); o.y = pk2(bflo(v.y) * rs * g0[2], bfhi(v.y) * rs * g0[3]);
;                 o.z = pk2(bflo(v.z) * rs * g1[0], bfhi(v.z) * rs * g1[1]); o.w = pk2(bflo(v.w) * rs * g1[2], bfhi(v.w) * rs * g1[3]); Qf[ks] = as_frag(o); }
;         }
;         __syncthreads();
;         const int nitem = item + (int)gridDim.x; const bool has_next = nitem < NITEM;
;         if (has_next) { it = dil_decode(nitem); dil_issue(Z, it, tid, kraw, vraw); }
	v_add_f32_e32 v68, v68, v69
	ds_bpermute_b32 v69, v165, v68
	s_waitcnt lgkmcnt(0)
	v_add_f32_e32 v68, v68, v69
	v_fmamk_f32 v68, v68, 0x3c000000, v243
	v_rsq_f32_e32 v68, v68
	s_nop 0
	v_mul_f32_e32 v210, 0x3db504f3, v68
	v_mul_f32_e32 v1, v210, v1
	v_mul_f32_e32 v68, v210, v117
	v_mul_f32_e32 v69, v210, v123
	v_mul_f32_e32 v70, v210, v127
	s_waitcnt vmcnt(6)
	v_mul_f32_e32 v1, v88, v1
	v_mul_f32_e32 v68, v89, v68
	v_mul_f32_e32 v69, v90, v69
	v_cvt_pk_bf16_f32 v68, v1, v68
	v_mul_f32_e32 v1, v91, v70
	v_cvt_pk_bf16_f32 v69, v69, v1
	v_mul_f32_e32 v1, v210, v129
	v_mul_f32_e32 v70, v210, v195
	v_mul_f32_e32 v1, v84, v1
	v_mul_f32_e32 v70, v85, v70
	v_cvt_pk_bf16_f32 v70, v1, v70
	v_mul_f32_e32 v1, v210, v200
	v_mul_f32_e32 v71, v210, v201
	v_mul_f32_e32 v1, v86, v1
	v_mul_f32_e32 v71, v87, v71
	v_cvt_pk_bf16_f32 v71, v1, v71
	v_mul_f32_e32 v1, v210, v202
	v_mul_f32_e32 v72, v210, v203
	s_waitcnt vmcnt(4)
	v_mul_f32_e32 v1, v1, v92
	v_mul_f32_e32 v72, v72, v93
	v_cvt_pk_bf16_f32 v72, v1, v72
	v_mul_f32_e32 v1, v210, v204
	v_mul_f32_e32 v73, v210, v205
	v_mul_f32_e32 v1, v1, v94
	v_mul_f32_e32 v73, v73, v95
	v_cvt_pk_bf16_f32 v73, v1, v73
	v_mul_f32_e32 v1, v210, v206
	v_mul_f32_e32 v74, v210, v207
	v_mul_f32_e32 v1, v1, v80
	v_mul_f32_e32 v74, v74, v81
	v_cvt_pk_bf16_f32 v74, v1, v74
	v_mul_f32_e32 v1, v210, v208
	v_mul_f32_e32 v75, v210, v209
	v_mul_f32_e32 v1, v1, v82
	v_mul_f32_e32 v75, v75, v83
	v_cvt_pk_bf16_f32 v75, v1, v75
	v_mul_f32_e32 v1, v210, v108
	v_mul_f32_e32 v2, v210, v2
	s_waitcnt vmcnt(2)
	v_mul_f32_e32 v1, v1, v76
	v_mul_f32_e32 v2, v2, v77
	v_cvt_pk_bf16_f32 v76, v1, v2
	v_mul_f32_e32 v1, v210, v110
	v_mul_f32_e32 v2, v210, v112
	v_mul_f32_e32 v1, v1, v78
	v_mul_f32_e32 v2, v2, v79
	v_cvt_pk_bf16_f32 v77, v1, v2
	v_mul_f32_e32 v1, v210, v114
	v_mul_f32_e32 v2, v210, v132
	v_mul_f32_e32 v1, v1, v96
	v_mul_f32_e32 v2, v2, v97
	v_cvt_pk_bf16_f32 v78, v1, v2
	v_mul_f32_e32 v1, v210, v134
	v_mul_f32_e32 v2, v210, v136
	v_mul_f32_e32 v1, v1, v98
	v_mul_f32_e32 v2, v2, v99
	v_cvt_pk_bf16_f32 v79, v1, v2
	v_mul_f32_e32 v1, v210, v109
	v_mul_f32_e32 v2, v210, v3
	s_waitcnt vmcnt(1)
	v_mul_f32_e32 v1, v1, v104
	v_mul_f32_e32 v2, v2, v105
	v_cvt_pk_bf16_f32 v80, v1, v2
	v_mul_f32_e32 v1, v210, v111
	v_mul_f32_e32 v2, v210, v113
	v_mul_f32_e32 v1, v1, v106
	v_mul_f32_e32 v2, v2, v107
	v_cvt_pk_bf16_f32 v81, v1, v2
	v_mul_f32_e32 v1, v210, v115
	v_mul_f32_e32 v2, v210, v133
	s_waitcnt vmcnt(0)
	v_mul_f32_e32 v1, v1, v100
	v_mul_f32_e32 v2, v2, v101
	v_cvt_pk_bf16_f32 v82, v1, v2
	v_mul_f32_e32 v1, v210, v135
	v_mul_f32_e32 v2, v210, v137
	v_mul_f32_e32 v1, v1, v102
	v_mul_f32_e32 v2, v2, v103
	v_cvt_pk_bf16_f32 v83, v1, v2
	s_cbranch_scc1 .LBB0_235
	s_ashr_i32 s8, s64, 5
	s_mul_hi_i32 s9, s8, 0x2aaaaaab
	s_lshr_b32 s12, s9, 31
	s_lshr_b32 s9, s9, 1
	s_add_i32 s9, s9, s12
	s_mul_i32 s9, s9, 12
	s_sub_i32 s17, s8, s9
	s_mul_hi_i32 s8, s64, 0x2aaaaaab
	s_lshr_b32 s12, s8, 31
	s_ashr_i32 s8, s8, 6
	s_and_b32 s9, s17, -4
	s_add_i32 s8, s8, s12
	s_and_b32 s12, s64, 31
	s_cmp_eq_u32 s9, 4
	s_cselect_b64 s[60:61], -1, 0
	s_and_b64 s[22:23], s[60:61], exec
	s_cselect_b32 s9, 2, 4
	s_cmp_lt_u32 s17, 4
	s_cselect_b64 s[62:63], -1, 0
	s_and_b64 s[22:23], s[62:63], exec
	s_cselect_b32 s9, 0, s9
	s_lshr_b32 s18, 32, s9
	s_lshr_b32 s22, 0x1000, s9
	s_sub_i32 s9, 5, s9
	s_add_i32 s18, s18, -1
	s_lshr_b32 s19, s12, s9
	s_and_b32 s9, s18, s12
	s_lshl_b32 s12, s9, 7
	s_ashr_i32 s9, s8, 31
	v_add_u32_e32 v2, s12, v139
	v_mov_b32_e32 v6, v0
	v_mov_b32_e32 v7, v0
	s_lshl_b64 s[52:53], s[8:9], 12
	v_cmp_lt_i32_e32 vcc, -1, v2
	v_cmp_gt_i32_e64 s[8:9], s22, v2
	v_mov_b32_e32 v4, v0
	v_mov_b32_e32 v5, v0
	v_mov_b64_e32 v[14:15], v[6:7]
	v_mov_b64_e32 v[10:11], v[6:7]
	s_or_b32 s52, s52, s19
	s_and_b64 s[24:25], vcc, s[8:9]
	v_mov_b64_e32 v[12:13], v[4:5]
	v_mov_b64_e32 v[8:9], v[4:5]
	s_and_saveexec_b64 s[8:9], s[24:25]
	s_cbranch_execz .LBB0_220
	s_and_b64 s[24:25], s[60:61], exec
	s_cselect_b32 s18, 2, 4
	s_and_b64 s[24:25], s[62:63], exec
	v_mov_b32_e32 v3, v0
	s_cselect_b32 s18, 0, s18
	v_lshlrev_b64 v[2:3], s18, v[2:3]
	v_lshl_add_u64 v[2:3], v[2:3], 0, s[52:53]
	v_mov_b64_e32 v[8:9], s[48:49]
	v_mad_u64_u32 v[8:9], s[24:25], v2, s78, v[8:9]
	v_mov_b32_e32 v2, v9
	v_mad_u64_u32 v[2:3], s[24:25], v3, s78, v[2:3]
	s_lshl_b32 s24, s17, 7
	v_mov_b32_e32 v9, v2
	s_ashr_i32 s25, s24, 31
	v_mov_b32_e32 v117, v0
	v_lshl_add_u64 v[2:3], s[24:25], 1, v[8:9]
	v_lshl_add_u64 v[2:3], v[2:3], 0, v[116:117]
	v_add_co_u32_e32 v8, vcc, 0x2000, v2
	s_nop 1
	v_addc_co_u32_e32 v9, vcc, 0, v3, vcc
	v_add_co_u32_e32 v2, vcc, 0x3000, v2
	s_nop 1
	v_addc_co_u32_e32 v3, vcc, 0, v3, vcc
	global_load_dwordx4 v[8:11], v[8:9], off offset:1024
	s_nop 0
	global_load_dwordx4 v[12:15], v[2:3], off

; template <bool STORE = true> DI void dil_attn_phase(int l, unsigned char* lds_g, LAS unsigned char* lds) {
;     ...
;         if (!has_next) break;
;         item = nitem;
;         __syncthreads();
.LBB0_310:
	s_or_b64 exec, exec, s[8:9]
	s_andn2_b64 vcc, exec, s[58:59]
	s_mov_b64 s[8:9], -1
	s_cbranch_vccnz .LBB0_214
	s_sub_i32 s64, s64, s14
	s_mov_b64 s[8:9], 0
	s_barrier
	s_branch .LBB0_214

;     DI bool next(int i, Unit& u) const {
;         const long L = (long)i * G + c; if (L >= nwg) return false;
;         int wgid = (int)L; { const int q = nwg / NXCD, r = nwg % NXCD, xcd = wgid % NXCD, off = wgid / NXCD; wgid = (xcd < r ? xcd * (q + 1) : r * (q + 1) + (xcd - r) * q) + off; }
;         const int nig = WGM * nN, gid = wgid / nig, fm = gid * WGM, gsz = (nM - fm) < WGM ? (nM - fm) : WGM;
;         u.pm = fm + ((wgid % nig) % gsz); u.pn = (wgid % nig) / gsz; return true;
;     }
.LBB0_765:
	s_ashr_i32 s8, s12, 3
	s_add_i32 s8, s23, s8
	s_ashr_i32 s9, s8, 31
	s_lshr_b32 s9, s9, 28
	s_add_i32 s9, s8, s9
	s_ashr_i32 s12, s9, 4
	s_and_b32 s9, s9, 0xfff0
	s_sub_i32 s8, s8, s9
	s_bfe_i32 s9, s8, 0x80000
	s_bfe_u32 s9, s9, 0x2000d
	s_add_i32 s9, s8, s9
	s_bfe_i32 s17, s9, 0x80000
	s_and_b32 s9, s9, 0xfc
	s_sub_i32 s8, s8, s9
	s_lshl_b32 s12, s12, 2
	s_sext_i32_i16 s17, s17
	s_sext_i32_i8 s8, s8
	s_add_i32 s72, s12, s8
	s_sub_i32 s72, 0xff, s72
	s_ashr_i32 s12, s17, 2

;     DI bool next(int i, Unit& u) const {
;         const long L = (long)i * G + c; if (L >= nwg) return false;
;         int wgid = (int)L; { const int q = nwg / NXCD, r = nwg % NXCD, xcd = wgid % NXCD, off = wgid / NXCD; wgid = (xcd < r ? xcd * (q + 1) : r * (q + 1) + (xcd - r) * q) + off; }
;         const int nig = WGM * nN, gid = wgid / nig, fm = gid * WGM, gsz = (nM - fm) < WGM ? (nM - fm) : WGM;
;         u.pm = fm + ((wgid % nig) % gsz); u.pn = (wgid % nig) / gsz; return true;
;     }
.LBB0_777:
	s_ashr_i32 s6, s22, 3
	s_add_i32 s6, s56, s6
	s_ashr_i32 s7, s6, 31
	s_lshr_b32 s7, s7, 28
	s_add_i32 s7, s6, s7
	s_ashr_i32 s18, s7, 4
	s_lshl_b32 s18, s18, 2
	s_sub_i32 s19, 0x100, s18
	s_min_i32 s19, s19, 4
	s_abs_i32 s22, s19
	v_cvt_f32_u32_e32 v2, s22
	s_sub_i32 s56, 0, s22
	s_and_b32 s7, s7, -16
	s_sub_i32 s6, s6, s7
	v_rcp_iflag_f32_e32 v2, v2
	s_abs_i32 s7, s6
	s_xor_b32 s23, s6, s19
	s_ashr_i32 s23, s23, 31
	v_mul_f32_e32 v2, 0x4f7ffffe, v2
	v_cvt_u32_f32_e32 v2, v2
	s_nop 0
	v_readfirstlane_b32 s57, v2
	s_mul_i32 s56, s56, s57
	s_mul_hi_u32 s56, s57, s56
	s_add_i32 s57, s57, s56
	s_mul_hi_u32 s56, s7, s57
	s_mul_i32 s57, s56, s22
	s_sub_i32 s7, s7, s57
	s_add_i32 s62, s56, 1
	s_sub_i32 s57, s7, s22
	s_cmp_ge_u32 s7, s22
	s_cselect_b32 s56, s62, s56
	s_cselect_b32 s7, s57, s7
	s_add_i32 s57, s56, 1
	s_cmp_ge_u32 s7, s22
	s_cselect_b32 s7, s57, s56
	s_xor_b32 s7, s7, s23
	s_sub_i32 s22, s7, s23
	s_mul_i32 s7, s22, s19
	s_sub_i32 s6, s6, s7
	s_add_i32 s23, s18, s6
	s_sub_i32 s23, 0xff, s23
